# hand-written rstd-scale (mode-2) GEMM epilogue with cached row statistics (mixer-in / KV / memkv GEMMs)
# speedup vs baseline: 1.0185x; 1.0005x over previous
.LBB0_534:
	s_andn2_b64 vcc, exec, s[10:11]
	s_cbranch_vccnz .LBB0_536
	v_ashrrev_i32_e32 v163, 31, v162
	s_cmp_eq_u32 s98, s20
	s_cbranch_scc1 .Lep2_fast
	s_mov_b32 s98, s20
	v_lshlrev_b64 v[164:165], 6, v[162:163]
	v_lshl_add_u64 v[164:165], v[156:157], 0, v[164:165]
	s_mov_b64 s[10:11], 0x2000
	global_load_dwordx4 v[190:193], v[164:165], off
	global_load_dwordx4 v[194:197], v[164:165], off offset:1024
	global_load_dwordx4 v[198:201], v[164:165], off offset:2048
	global_load_dwordx4 v[202:205], v[164:165], off offset:3072
	v_lshl_add_u64 v[166:167], v[164:165], 0, s[10:11]
	global_load_dwordx4 v[206:209], v[166:167], off
	global_load_dwordx4 v[210:213], v[166:167], off offset:1024
	global_load_dwordx4 v[214:217], v[166:167], off offset:2048
	global_load_dwordx4 v[218:221], v[166:167], off offset:3072
	v_mov_b32_e32 v173, s56
	s_waitcnt vmcnt(0)
	v_add_f32_e32 v190, v190, v191
	v_add_f32_e32 v194, v194, v195
	v_add_f32_e32 v198, v198, v199
	v_add_f32_e32 v202, v202, v203
	v_add_f32_e32 v206, v206, v207
	v_add_f32_e32 v210, v210, v211
	v_add_f32_e32 v214, v214, v215
	v_add_f32_e32 v218, v218, v219
	v_add_f32_e32 v192, v192, v193
	v_add_f32_e32 v196, v196, v197
	v_add_f32_e32 v200, v200, v201
	v_add_f32_e32 v204, v204, v205
	v_add_f32_e32 v208, v208, v209
	v_add_f32_e32 v212, v212, v213
	v_add_f32_e32 v216, v216, v217
	v_add_f32_e32 v220, v220, v221
	v_add_f32_e32 v242, v190, v192
	v_add_f32_e32 v243, v194, v196
	v_add_f32_e32 v244, v198, v200
	v_add_f32_e32 v245, v202, v204
	v_add_f32_e32 v246, v206, v208
	v_add_f32_e32 v247, v210, v212
	v_add_f32_e32 v248, v214, v216
	v_add_f32_e32 v249, v218, v220
	v_mov_b32_e32 v135, v242
	v_mov_b32_e32 v136, v243
	v_mov_b32_e32 v137, v244
	v_mov_b32_e32 v138, v245
	v_mov_b32_e32 v139, v246
	v_mov_b32_e32 v140, v247
	v_mov_b32_e32 v141, v248
	v_mov_b32_e32 v142, v249
	s_nop 1
	v_permlane16_swap_b32_e32 v242, v135
	v_permlane16_swap_b32_e32 v243, v136
	v_permlane16_swap_b32_e32 v244, v137
	v_permlane16_swap_b32_e32 v245, v138
	v_permlane16_swap_b32_e32 v246, v139
	v_permlane16_swap_b32_e32 v247, v140
	v_permlane16_swap_b32_e32 v248, v141
	v_permlane16_swap_b32_e32 v249, v142
	v_add_f32_e32 v242, v242, v135
	v_add_f32_e32 v243, v243, v136
	v_add_f32_e32 v244, v244, v137
	v_add_f32_e32 v245, v245, v138
	v_add_f32_e32 v246, v246, v139
	v_add_f32_e32 v247, v247, v140
	v_add_f32_e32 v248, v248, v141
	v_add_f32_e32 v249, v249, v142
	v_mov_b32_e32 v135, v242
	v_mov_b32_e32 v136, v243
	v_mov_b32_e32 v137, v244
	v_mov_b32_e32 v138, v245
	v_mov_b32_e32 v139, v246
	v_mov_b32_e32 v140, v247
	v_mov_b32_e32 v141, v248
	v_mov_b32_e32 v142, v249
	s_nop 1
	v_permlane32_swap_b32_e32 v242, v135
	v_permlane32_swap_b32_e32 v243, v136
	v_permlane32_swap_b32_e32 v244, v137
	v_permlane32_swap_b32_e32 v245, v138
	v_permlane32_swap_b32_e32 v246, v139
	v_permlane32_swap_b32_e32 v247, v140
	v_permlane32_swap_b32_e32 v248, v141
	v_permlane32_swap_b32_e32 v249, v142
	v_add_f32_e32 v242, v242, v135
	v_add_f32_e32 v243, v243, v136
	v_add_f32_e32 v244, v244, v137
	v_add_f32_e32 v245, v245, v138
	v_add_f32_e32 v246, v246, v139
	v_add_f32_e32 v247, v247, v140
	v_add_f32_e32 v248, v248, v141
	v_add_f32_e32 v249, v249, v142
	v_fma_f32 v242, v242, s54, v173
	v_fma_f32 v243, v243, s54, v173
	v_fma_f32 v244, v244, s54, v173
	v_fma_f32 v245, v245, s54, v173
	v_fma_f32 v246, v246, s54, v173
	v_fma_f32 v247, v247, s54, v173
	v_fma_f32 v248, v248, s54, v173
	v_fma_f32 v249, v249, s54, v173
	v_rsq_f32_e32 v250, v242
	v_rsq_f32_e32 v251, v243
	v_rsq_f32_e32 v252, v244
	v_rsq_f32_e32 v253, v245
	v_rsq_f32_e32 v168, v246
	v_rsq_f32_e32 v170, v247
	v_rsq_f32_e32 v176, v248
	v_rsq_f32_e32 v178, v249
	s_nop 0
.Lep2_fast:
	v_mad_u64_u32 v[174:175], s[10:11], s28, v162, 0
	v_lshl_or_b32 v164, s25, 8, v186
	v_mov_b32_e32 v165, 0
	s_lshl_b64 s[78:79], s[28:29], 5
	s_lshl_b64 s[84:85], s[28:29], 8
	v_lshl_add_u64 v[174:175], v[174:175], 0, v[164:165]
	v_lshl_add_u64 v[174:175], v[174:175], 1, s[70:71]
	v_lshl_add_u64 v[166:167], v[174:175], 0, s[84:85]
	v_mul_f32_e32 v190, v250, v124
	v_mul_f32_e32 v191, v250, v125
	v_mul_f32_e32 v192, v250, v126
	v_mul_f32_e32 v193, v250, v127
	v_mul_f32_e32 v194, v250, v116
	v_mul_f32_e32 v195, v250, v117
	v_mul_f32_e32 v196, v250, v118
	v_mul_f32_e32 v197, v250, v119
	v_cvt_pk_bf16_f32 v190, v190, v191
	v_cvt_pk_bf16_f32 v191, v192, v193
	v_cvt_pk_bf16_f32 v192, v194, v195
	v_cvt_pk_bf16_f32 v193, v196, v197
	global_store_dwordx4 v[174:175], v[190:193], off
	v_mul_f32_e32 v198, v250, v108
	v_mul_f32_e32 v199, v250, v109
	v_mul_f32_e32 v200, v250, v110
	v_mul_f32_e32 v201, v250, v111
	v_mul_f32_e32 v202, v250, v100
	v_mul_f32_e32 v203, v250, v101
	v_mul_f32_e32 v204, v250, v102
	v_mul_f32_e32 v205, v250, v103
	v_cvt_pk_bf16_f32 v198, v198, v199
	v_cvt_pk_bf16_f32 v199, v200, v201
	v_cvt_pk_bf16_f32 v200, v202, v203
	v_cvt_pk_bf16_f32 v201, v204, v205
	global_store_dwordx4 v[174:175], v[198:201], off offset:256
	v_lshl_add_u64 v[174:175], v[174:175], 0, s[78:79]
	v_mul_f32_e32 v206, v251, v120
	v_mul_f32_e32 v207, v251, v121
	v_mul_f32_e32 v208, v251, v122
	v_mul_f32_e32 v209, v251, v123
	v_mul_f32_e32 v210, v251, v112
	v_mul_f32_e32 v211, v251, v113
	v_mul_f32_e32 v212, v251, v114
	v_mul_f32_e32 v213, v251, v115
	v_cvt_pk_bf16_f32 v206, v206, v207
	v_cvt_pk_bf16_f32 v207, v208, v209
	v_cvt_pk_bf16_f32 v208, v210, v211
	v_cvt_pk_bf16_f32 v209, v212, v213
	global_store_dwordx4 v[174:175], v[206:209], off
	v_mul_f32_e32 v214, v251, v104
	v_mul_f32_e32 v215, v251, v105
	v_mul_f32_e32 v216, v251, v106
	v_mul_f32_e32 v217, v251, v107
	v_mul_f32_e32 v218, v251, v96
	v_mul_f32_e32 v219, v251, v97
	v_mul_f32_e32 v220, v251, v98
	v_mul_f32_e32 v221, v251, v99
	v_cvt_pk_bf16_f32 v214, v214, v215
	v_cvt_pk_bf16_f32 v215, v216, v217
	v_cvt_pk_bf16_f32 v216, v218, v219
	v_cvt_pk_bf16_f32 v217, v220, v221
	global_store_dwordx4 v[174:175], v[214:217], off offset:256
	v_lshl_add_u64 v[174:175], v[174:175], 0, s[78:79]
	v_mul_f32_e32 v190, v252, v92
	v_mul_f32_e32 v191, v252, v93
	v_mul_f32_e32 v192, v252, v94
	v_mul_f32_e32 v193, v252, v95
	v_mul_f32_e32 v194, v252, v84
	v_mul_f32_e32 v195, v252, v85
	v_mul_f32_e32 v196, v252, v86
	v_mul_f32_e32 v197, v252, v87
	v_cvt_pk_bf16_f32 v190, v190, v191
	v_cvt_pk_bf16_f32 v191, v192, v193
	v_cvt_pk_bf16_f32 v192, v194, v195
	v_cvt_pk_bf16_f32 v193, v196, v197
	global_store_dwordx4 v[174:175], v[190:193], off
	v_mul_f32_e32 v198, v252, v76
	v_mul_f32_e32 v199, v252, v77
	v_mul_f32_e32 v200, v252, v78
	v_mul_f32_e32 v201, v252, v79
	v_mul_f32_e32 v202, v252, v68
	v_mul_f32_e32 v203, v252, v69
	v_mul_f32_e32 v204, v252, v70
	v_mul_f32_e32 v205, v252, v71
	v_cvt_pk_bf16_f32 v198, v198, v199
	v_cvt_pk_bf16_f32 v199, v200, v201
	v_cvt_pk_bf16_f32 v200, v202, v203
	v_cvt_pk_bf16_f32 v201, v204, v205
	global_store_dwordx4 v[174:175], v[198:201], off offset:256
	v_lshl_add_u64 v[174:175], v[174:175], 0, s[78:79]
	v_mul_f32_e32 v206, v253, v88
	v_mul_f32_e32 v207, v253, v89
	v_mul_f32_e32 v208, v253, v90
	v_mul_f32_e32 v209, v253, v91
	v_mul_f32_e32 v210, v253, v80
	v_mul_f32_e32 v211, v253, v81
	v_mul_f32_e32 v212, v253, v82
	v_mul_f32_e32 v213, v253, v83
	v_cvt_pk_bf16_f32 v206, v206, v207
	v_cvt_pk_bf16_f32 v207, v208, v209
	v_cvt_pk_bf16_f32 v208, v210, v211
	v_cvt_pk_bf16_f32 v209, v212, v213
	global_store_dwordx4 v[174:175], v[206:209], off
	v_mul_f32_e32 v214, v253, v72
	v_mul_f32_e32 v215, v253, v73
	v_mul_f32_e32 v216, v253, v74
	v_mul_f32_e32 v217, v253, v75
	v_mul_f32_e32 v218, v253, v64
	v_mul_f32_e32 v219, v253, v65
	v_mul_f32_e32 v220, v253, v66
	v_mul_f32_e32 v221, v253, v67
	v_cvt_pk_bf16_f32 v214, v214, v215
	v_cvt_pk_bf16_f32 v215, v216, v217
	v_cvt_pk_bf16_f32 v216, v218, v219
	v_cvt_pk_bf16_f32 v217, v220, v221
	global_store_dwordx4 v[174:175], v[214:217], off offset:256
	v_mul_f32_e32 v190, v168, v60
	v_mul_f32_e32 v191, v168, v61
	v_mul_f32_e32 v192, v168, v62
	v_mul_f32_e32 v193, v168, v63
	v_mul_f32_e32 v194, v168, v56
	v_mul_f32_e32 v195, v168, v57
	v_mul_f32_e32 v196, v168, v58
	v_mul_f32_e32 v197, v168, v59
	v_cvt_pk_bf16_f32 v190, v190, v191
	v_cvt_pk_bf16_f32 v191, v192, v193
	v_cvt_pk_bf16_f32 v192, v194, v195
	v_cvt_pk_bf16_f32 v193, v196, v197
	global_store_dwordx4 v[166:167], v[190:193], off
	v_mul_f32_e32 v198, v168, v44
	v_mul_f32_e32 v199, v168, v45
	v_mul_f32_e32 v200, v168, v46
	v_mul_f32_e32 v201, v168, v47
	v_mul_f32_e32 v202, v168, v36
	v_mul_f32_e32 v203, v168, v37
	v_mul_f32_e32 v204, v168, v38
	v_mul_f32_e32 v205, v168, v39
	v_cvt_pk_bf16_f32 v198, v198, v199
	v_cvt_pk_bf16_f32 v199, v200, v201
	v_cvt_pk_bf16_f32 v200, v202, v203
	v_cvt_pk_bf16_f32 v201, v204, v205
	global_store_dwordx4 v[166:167], v[198:201], off offset:256
	v_lshl_add_u64 v[166:167], v[166:167], 0, s[78:79]
	v_mul_f32_e32 v206, v170, v52
	v_mul_f32_e32 v207, v170, v53
	v_mul_f32_e32 v208, v170, v54
	v_mul_f32_e32 v209, v170, v55
	v_mul_f32_e32 v210, v170, v48
	v_mul_f32_e32 v211, v170, v49
	v_mul_f32_e32 v212, v170, v50
	v_mul_f32_e32 v213, v170, v51
	v_cvt_pk_bf16_f32 v206, v206, v207
	v_cvt_pk_bf16_f32 v207, v208, v209
	v_cvt_pk_bf16_f32 v208, v210, v211
	v_cvt_pk_bf16_f32 v209, v212, v213
	global_store_dwordx4 v[166:167], v[206:209], off
	v_mul_f32_e32 v214, v170, v40
	v_mul_f32_e32 v215, v170, v41
	v_mul_f32_e32 v216, v170, v42
	v_mul_f32_e32 v217, v170, v43
	v_mul_f32_e32 v218, v170, v32
	v_mul_f32_e32 v219, v170, v33
	v_mul_f32_e32 v220, v170, v34
	v_mul_f32_e32 v221, v170, v35
	v_cvt_pk_bf16_f32 v214, v214, v215
	v_cvt_pk_bf16_f32 v215, v216, v217
	v_cvt_pk_bf16_f32 v216, v218, v219
	v_cvt_pk_bf16_f32 v217, v220, v221
	global_store_dwordx4 v[166:167], v[214:217], off offset:256
	v_lshl_add_u64 v[166:167], v[166:167], 0, s[78:79]
	v_mul_f32_e32 v190, v176, v28
	v_mul_f32_e32 v191, v176, v29
	v_mul_f32_e32 v192, v176, v30
	v_mul_f32_e32 v193, v176, v31
	v_mul_f32_e32 v194, v176, v20
	v_mul_f32_e32 v195, v176, v21
	v_mul_f32_e32 v196, v176, v22
	v_mul_f32_e32 v197, v176, v23
	v_cvt_pk_bf16_f32 v190, v190, v191
	v_cvt_pk_bf16_f32 v191, v192, v193
	v_cvt_pk_bf16_f32 v192, v194, v195
	v_cvt_pk_bf16_f32 v193, v196, v197
	global_store_dwordx4 v[166:167], v[190:193], off
	v_mul_f32_e32 v198, v176, v12
	v_mul_f32_e32 v199, v176, v13
	v_mul_f32_e32 v200, v176, v14
	v_mul_f32_e32 v201, v176, v15
	v_mul_f32_e32 v202, v176, v4
	v_mul_f32_e32 v203, v176, v5
	v_mul_f32_e32 v204, v176, v6
	v_mul_f32_e32 v205, v176, v7
	v_cvt_pk_bf16_f32 v198, v198, v199
	v_cvt_pk_bf16_f32 v199, v200, v201
	v_cvt_pk_bf16_f32 v200, v202, v203
	v_cvt_pk_bf16_f32 v201, v204, v205
	global_store_dwordx4 v[166:167], v[198:201], off offset:256
	v_lshl_add_u64 v[166:167], v[166:167], 0, s[78:79]
	v_mul_f32_e32 v206, v178, v24
	v_mul_f32_e32 v207, v178, v25
	v_mul_f32_e32 v208, v178, v26
	v_mul_f32_e32 v209, v178, v27
	v_mul_f32_e32 v210, v178, v16
	v_mul_f32_e32 v211, v178, v17
	v_mul_f32_e32 v212, v178, v18
	v_mul_f32_e32 v213, v178, v19
	v_cvt_pk_bf16_f32 v206, v206, v207
	v_cvt_pk_bf16_f32 v207, v208, v209
	v_cvt_pk_bf16_f32 v208, v210, v211
	v_cvt_pk_bf16_f32 v209, v212, v213
	global_store_dwordx4 v[166:167], v[206:209], off
	v_mul_f32_e32 v214, v178, v8
	v_mul_f32_e32 v215, v178, v9
	v_mul_f32_e32 v216, v178, v10
	v_mul_f32_e32 v217, v178, v11
	v_mul_f32_e32 v218, v178, v0
	v_mul_f32_e32 v219, v178, v1
	v_mul_f32_e32 v220, v178, v2
	v_mul_f32_e32 v221, v178, v3
	v_cvt_pk_bf16_f32 v214, v214, v215
	v_cvt_pk_bf16_f32 v215, v216, v217
	v_cvt_pk_bf16_f32 v216, v218, v219
	v_cvt_pk_bf16_f32 v217, v220, v221
	global_store_dwordx4 v[166:167], v[214:217], off offset:256
	s_branch .LBB0_514
